# diff attention loop second half hand-rewritten: softmax maps split in time, P.V of map 0 beside map 1 softmax, map 1 P.V deferred to next iteration head beside the LDS-DMA issue
# speedup vs baseline: 1.0137x; 1.0137x over previous
.LBB0_1618:
	s_or_b64 exec, exec, s[6:7]
	s_waitcnt vmcnt(8) lgkmcnt(0)
	s_lshl_b32 s5, s46, 6
	s_mov_b32 s72, 0x20000
	s_mov_b32 s73, 0
	s_lshl_b32 s46, s5, 1
	s_barrier
	s_mov_b32 s98, 0
	s_branch .LBB0_1621

.LBB0_1621:
	s_cmp_lg_u32 s98, 0
	s_cbranch_scc0 .Ldf_plain
	s_mov_b32 s5, s73
	s_add_i32 s5, s5, 4
	s_min_u32 s5, s5, s50
	v_mfma_f32_16x16x32_bf16 v[72:75], v[182:185], v[246:249], v[72:75]
	v_mad_u64_u32 v[2:3], s[6:7], s5, v144, v[112:113]
	s_lshl_b32 s10, s5, 6
	v_mfma_f32_16x16x32_bf16 v[64:67], v[186:189], v[246:249], v[64:67]
	s_and_b32 s5, s72, 0x18000
	s_add_i32 s5, s5, s51
	v_mfma_f32_16x16x32_bf16 v[56:59], v[190:193], v[246:249], v[56:59]
	s_mov_b32 s6, m0
	s_mov_b32 m0, s5
	v_mfma_f32_16x16x32_bf16 v[48:51], v[194:197], v[246:249], v[48:51]
	s_nop 0
	global_load_lds_dwordx4 v[2:3], off
	v_mfma_f32_16x16x32_bf16 v[40:43], v[198:201], v[246:249], v[40:43]
	s_mov_b32 m0, s6
	v_lshl_add_u64 v[2:3], v[2:3], 0, s[78:79]
	v_mfma_f32_16x16x32_bf16 v[28:31], v[202:205], v[246:249], v[28:31]
	s_add_i32 s6, s5, 0x2000
	v_mfma_f32_16x16x32_bf16 v[20:23], v[206:209], v[246:249], v[20:23]
	s_mov_b32 s7, m0
	s_mov_b32 m0, s6
	v_mfma_f32_16x16x32_bf16 v[80:83], v[210:213], v[246:249], v[80:83]
	s_nop 0
	global_load_lds_dwordx4 v[2:3], off
	v_mfma_f32_16x16x32_bf16 v[76:79], v[120:123], v[246:249], v[76:79]
	s_mov_b32 m0, s7
	v_lshl_add_u64 v[92:93], s[10:11], 1, v[114:115]
	v_mfma_f32_16x16x32_bf16 v[72:75], v[214:217], v[250:253], v[72:75]
	s_add_i32 s6, s5, 0x4000
	v_mfma_f32_16x16x32_bf16 v[64:67], v[218:221], v[250:253], v[64:67]
	s_mov_b32 s7, m0
	s_mov_b32 m0, s6
	v_mfma_f32_16x16x32_bf16 v[56:59], v[222:225], v[250:253], v[56:59]
	s_nop 0
	global_load_lds_dwordx4 v[92:93], off
	s_mov_b32 m0, s7
	v_mfma_f32_16x16x32_bf16 v[48:51], v[226:229], v[250:253], v[48:51]
	s_mov_b32 s47, s11
	v_mfma_f32_16x16x32_bf16 v[40:43], v[230:233], v[250:253], v[40:43]
	v_lshl_add_u64 v[2:3], v[92:93], 0, s[46:47]
	s_addk_i32 s5, 0x6000
	v_mfma_f32_16x16x32_bf16 v[28:31], v[234:237], v[250:253], v[28:31]
	s_mov_b32 s6, m0
	s_mov_b32 m0, s5
	v_mfma_f32_16x16x32_bf16 v[20:23], v[238:241], v[250:253], v[20:23]
	s_nop 0
	global_load_lds_dwordx4 v[2:3], off
	v_mfma_f32_16x16x32_bf16 v[80:83], v[242:245], v[250:253], v[80:83]
	s_mov_b32 m0, s6
	v_mfma_f32_16x16x32_bf16 v[76:79], v[120:123], v[250:253], v[76:79]
	s_mov_b32 s98, 0
	s_branch .Ldf_join

.Ldf_join:
	s_add_i32 s73, s73, 1
	v_cmp_lt_u32_e32 vcc, s73, v109
	s_and_saveexec_b64 s[48:49], vcc
	s_cbranch_execz .LBB0_1620
	s_add_i32 s5, s72, 0xfffe8000
	s_and_b32 s5, s5, 0x18000
	s_add_i32 s5, s5, 0
	v_add_u32_e32 v2, s5, v152
	v_add_u32_e32 v3, v2, v155
	v_add_u32_e32 v117, v2, v156
	ds_read_b128 v[92:95], v3
	ds_read_b128 v[96:99], v3 offset:4096
	ds_read_b128 v[100:103], v117
	ds_read_b128 v[104:107], v117 offset:4096
	s_waitcnt lgkmcnt(3)
	v_mfma_f32_16x16x32_bf16 v[92:95], v[92:95], v[4:7], 0
	s_waitcnt lgkmcnt(2)
	v_mfma_f32_16x16x32_bf16 v[96:99], v[96:99], v[4:7], 0
	s_waitcnt lgkmcnt(1)
	v_mfma_f32_16x16x32_bf16 v[92:95], v[100:103], v[8:11], v[92:95]
	s_waitcnt lgkmcnt(0)
	v_mfma_f32_16x16x32_bf16 v[96:99], v[104:107], v[8:11], v[96:99]
	ds_read_b128 v[100:103], v3 offset:8192
	ds_read_b128 v[104:107], v3 offset:12288
	ds_read_b128 v[118:121], v117 offset:8192
	ds_read_b128 v[122:125], v117 offset:12288
	v_add_u32_e32 v3, v2, v157
	s_waitcnt lgkmcnt(3)
	v_mfma_f32_16x16x32_bf16 v[100:103], v[100:103], v[4:7], 0
	v_add_u32_e32 v2, v2, v158
	v_fma_f32 v126, v94, s24, -v0
	v_fma_f32 v127, v95, s24, -v0
	v_fma_f32 v130, v98, s24, -v0
	v_fma_f32 v131, v99, s24, -v0
	s_waitcnt lgkmcnt(2)
	v_mfma_f32_16x16x32_bf16 v[104:107], v[104:107], v[4:7], 0
	v_fma_f32 v128, v96, s24, -v0
	v_fma_f32 v129, v97, s24, -v0
	s_waitcnt lgkmcnt(1)
	v_mfma_f32_16x16x32_bf16 v[100:103], v[118:121], v[8:11], v[100:103]
	ds_read_b128 v[118:121], v3
	ds_read_b128 v[132:135], v3 offset:4096
	ds_read_b128 v[136:139], v2
	ds_read_b128 v[162:165], v2 offset:4096
	ds_read_b128 v[166:169], v3 offset:8192
	ds_read_b128 v[170:173], v3 offset:12288
	ds_read_b128 v[174:177], v2 offset:8192
	ds_read_b128 v[178:181], v2 offset:12288
	s_waitcnt lgkmcnt(8)
	v_mfma_f32_16x16x32_bf16 v[104:107], v[122:125], v[8:11], v[104:107]
	v_fma_f32 v124, v92, s24, -v0
	v_fma_f32 v125, v93, s24, -v0
	v_fma_f32 v122, v102, s24, -v0
	v_fma_f32 v123, v103, s24, -v0
	s_waitcnt lgkmcnt(7)
	v_mfma_f32_16x16x32_bf16 v[92:95], v[118:121], v[12:15], 0
	v_fma_f32 v118, v100, s24, -v0
	v_fma_f32 v119, v101, s24, -v0
	s_nop 0
	v_fma_f32 v2, v106, s24, -v0
	v_fma_f32 v3, v107, s24, -v0
	v_max_f32_e32 v100, v126, v127
	v_max_f32_e32 v101, v130, v131
	v_fma_f32 v120, v104, s24, -v0
	v_fma_f32 v121, v105, s24, -v0
	v_max3_f32 v100, v124, v125, v100
	v_max3_f32 v101, v128, v129, v101
	v_max_f32_e32 v105, v122, v123
	v_max_f32_e32 v106, v2, v3
	v_max3_f32 v104, v100, s25, v101
	v_max3_f32 v105, v118, v119, v105
	v_max3_f32 v106, v120, v121, v106
	v_max3_f32 v117, v104, v105, v106
	v_mov_b32_e32 v104, v117
	s_waitcnt lgkmcnt(6)
	v_mfma_f32_16x16x32_bf16 v[96:99], v[132:135], v[12:15], 0
	v_permlane16_swap_b32_e32 v104, v117
	s_waitcnt lgkmcnt(0)
	v_max_f32_e32 v117, v117, v104
	v_mfma_f32_16x16x32_bf16 v[100:103], v[166:169], v[12:15], 0
	v_mov_b32_e32 v132, v117
	s_nop 1
	v_permlane32_swap_b32_e32 v132, v117
	v_mfma_f32_16x16x32_bf16 v[104:107], v[170:173], v[12:15], 0
	v_max_f32_e32 v117, v117, v132
	v_cmp_lt_f32_e32 vcc, s70, v117
	v_mfma_f32_16x16x32_bf16 v[92:95], v[136:139], v[16:19], v[92:95]
	v_mfma_f32_16x16x32_bf16 v[96:99], v[162:165], v[16:19], v[96:99]
	v_mfma_f32_16x16x32_bf16 v[100:103], v[174:177], v[16:19], v[100:103]
	v_mfma_f32_16x16x32_bf16 v[104:107], v[178:181], v[16:19], v[104:107]
	s_cbranch_vccz .LBB0_1624
	v_max_f32_e32 v117, v117, v117
	v_max_f32_e32 v117, 0, v117
	v_exp_f32_e64 v132, -v117
	v_add_f32_e32 v0, v0, v117
	v_sub_f32_e32 v124, v124, v117
	v_sub_f32_e32 v125, v125, v117
	v_pk_mul_f32 v[86:87], v[86:87], v[132:133] op_sel_hi:[1,0]
	v_pk_mul_f32 v[84:85], v[84:85], v[132:133] op_sel_hi:[1,0]
	v_pk_mul_f32 v[26:27], v[26:27], v[132:133] op_sel_hi:[1,0]
	v_pk_mul_f32 v[24:25], v[24:25], v[132:133] op_sel_hi:[1,0]
	v_pk_mul_f32 v[34:35], v[34:35], v[132:133] op_sel_hi:[1,0]
	v_pk_mul_f32 v[32:33], v[32:33], v[132:133] op_sel_hi:[1,0]
	v_pk_mul_f32 v[38:39], v[38:39], v[132:133] op_sel_hi:[1,0]
	v_pk_mul_f32 v[36:37], v[36:37], v[132:133] op_sel_hi:[1,0]
	v_pk_mul_f32 v[46:47], v[46:47], v[132:133] op_sel_hi:[1,0]
	v_pk_mul_f32 v[44:45], v[44:45], v[132:133] op_sel_hi:[1,0]
	v_pk_mul_f32 v[54:55], v[54:55], v[132:133] op_sel_hi:[1,0]
	v_pk_mul_f32 v[52:53], v[52:53], v[132:133] op_sel_hi:[1,0]
	v_pk_mul_f32 v[62:63], v[62:63], v[132:133] op_sel_hi:[1,0]
	v_pk_mul_f32 v[60:61], v[60:61], v[132:133] op_sel_hi:[1,0]
	v_pk_mul_f32 v[70:71], v[70:71], v[132:133] op_sel_hi:[1,0]
	v_pk_mul_f32 v[68:69], v[68:69], v[132:133] op_sel_hi:[1,0]
	v_pk_mul_f32 v[90:91], v[90:91], v[132:133] op_sel_hi:[1,0]
	v_pk_mul_f32 v[88:89], v[88:89], v[132:133] op_sel_hi:[1,0]
	v_sub_f32_e32 v126, v126, v117
	v_sub_f32_e32 v127, v127, v117
	v_sub_f32_e32 v128, v128, v117
	v_sub_f32_e32 v129, v129, v117
	v_sub_f32_e32 v130, v130, v117
	v_sub_f32_e32 v131, v131, v117
	v_sub_f32_e32 v118, v118, v117
	v_sub_f32_e32 v119, v119, v117
	v_sub_f32_e32 v122, v122, v117
	v_sub_f32_e32 v123, v123, v117
	v_sub_f32_e32 v120, v120, v117
	v_sub_f32_e32 v121, v121, v117
	v_sub_f32_e32 v2, v2, v117
	v_sub_f32_e32 v3, v3, v117
.LBB0_1624:
	v_add_u32_e32 v136, s5, v153
	v_add_u32_e32 v137, v136, v160
	v_add_u32_e32 v136, v136, v159
	ds_read_b128 v[182:185], v136 offset:16384
	ds_read_b128 v[186:189], v136 offset:18432
	v_exp_f32_e32 v124, v124
	v_exp_f32_e32 v125, v125
	v_exp_f32_e32 v126, v126
	v_exp_f32_e32 v127, v127
	v_exp_f32_e32 v128, v128
	v_exp_f32_e32 v129, v129
	v_exp_f32_e32 v130, v130
	v_exp_f32_e32 v131, v131
	v_exp_f32_e32 v118, v118
	v_exp_f32_e32 v119, v119
	v_exp_f32_e32 v122, v122
	v_exp_f32_e32 v123, v123
	v_exp_f32_e32 v120, v120
	v_exp_f32_e32 v121, v121
	v_exp_f32_e32 v2, v2
	v_exp_f32_e32 v3, v3
	v_cvt_pk_bf16_f32 v124, v124, v125
	v_cvt_pk_bf16_f32 v125, v126, v127
	v_cvt_pk_bf16_f32 v126, v128, v129
	v_cvt_pk_bf16_f32 v127, v130, v131
	v_cvt_pk_bf16_f32 v128, v118, v119
	v_cvt_pk_bf16_f32 v129, v122, v123
	v_cvt_pk_bf16_f32 v130, v120, v121
	v_cvt_pk_bf16_f32 v131, v2, v3
	v_mov_b32_e32 v120, s4
	v_mov_b32_e32 v121, s4
	v_mov_b32_e32 v122, s4
	v_mov_b32_e32 v123, s4
	ds_read_b128 v[190:193], v136 offset:20480
	s_waitcnt lgkmcnt(2)
	v_mfma_f32_16x16x32_bf16 v[68:71], v[182:185], v[124:127], v[68:71]
	v_fma_f32 v92, v92, s24, -v116
	v_fma_f32 v93, v93, s24, -v116
	v_fma_f32 v94, v94, s24, -v116
	v_fma_f32 v95, v95, s24, -v116
	ds_read_b128 v[194:197], v136 offset:22528
	s_waitcnt lgkmcnt(2)
	v_mfma_f32_16x16x32_bf16 v[60:63], v[186:189], v[124:127], v[60:63]
	v_fma_f32 v96, v96, s24, -v116
	v_fma_f32 v97, v97, s24, -v116
	v_fma_f32 v98, v98, s24, -v116
	ds_read_b128 v[198:201], v136 offset:24576
	s_waitcnt lgkmcnt(2)
	v_mfma_f32_16x16x32_bf16 v[52:55], v[190:193], v[124:127], v[52:55]
	v_fma_f32 v99, v99, s24, -v116
	v_fma_f32 v100, v100, s24, -v116
	v_fma_f32 v101, v101, s24, -v116
	v_fma_f32 v102, v102, s24, -v116
	ds_read_b128 v[202:205], v136 offset:26624
	s_waitcnt lgkmcnt(2)
	v_mfma_f32_16x16x32_bf16 v[44:47], v[194:197], v[124:127], v[44:47]
	v_fma_f32 v103, v103, s24, -v116
	v_fma_f32 v104, v104, s24, -v116
	v_fma_f32 v105, v105, s24, -v116
	v_fma_f32 v106, v106, s24, -v116
	ds_read_b128 v[206:209], v136 offset:28672
	s_waitcnt lgkmcnt(2)
	v_mfma_f32_16x16x32_bf16 v[36:39], v[198:201], v[124:127], v[36:39]
	v_fma_f32 v107, v107, s24, -v116
	v_max3_f32 v132, v92, v93, v94
	v_max3_f32 v133, v95, v96, v97
	ds_read_b128 v[210:213], v136 offset:30720
	s_waitcnt lgkmcnt(2)
	v_mfma_f32_16x16x32_bf16 v[32:35], v[202:205], v[124:127], v[32:35]
	v_max3_f32 v134, v98, v99, v100
	v_max3_f32 v135, v101, v102, v103
	v_max3_f32 v138, v104, v105, v106
	v_max3_f32 v132, v132, v133, v134
	ds_read_b128 v[214:217], v137 offset:16384
	s_waitcnt lgkmcnt(2)
	v_mfma_f32_16x16x32_bf16 v[24:27], v[206:209], v[124:127], v[24:27]
	v_max3_f32 v135, v135, v138, v107
	v_max3_f32 v132, v132, s25, v135
	v_mov_b32_e32 v133, v132
	s_nop 1
	ds_read_b128 v[218:221], v137 offset:18432
	s_waitcnt lgkmcnt(2)
	v_mfma_f32_16x16x32_bf16 v[84:87], v[210:213], v[124:127], v[84:87]
	v_permlane16_swap_b32_e32 v133, v132
	v_max_f32_e32 v132, v132, v133
	v_mov_b32_e32 v133, v132
	v_mfma_f32_16x16x32_bf16 v[88:91], v[120:123], v[124:127], v[88:91]
	s_nop 1
	v_permlane32_swap_b32_e32 v133, v132
	v_max_f32_e32 v132, v132, v133
	v_cmp_lt_f32_e32 vcc, s70, v132
	s_cbranch_vccz .Lds_join
	v_max_f32_e32 v132, v132, v132
	v_max_f32_e32 v133, 0, v132
	v_exp_f32_e64 v134, -v133
	v_add_f32_e32 v116, v116, v133
	v_sub_f32_e32 v92, v92, v133
	v_sub_f32_e32 v93, v93, v133
	v_sub_f32_e32 v94, v94, v133
	v_sub_f32_e32 v95, v95, v133
	v_sub_f32_e32 v96, v96, v133
	v_sub_f32_e32 v97, v97, v133
	v_sub_f32_e32 v98, v98, v133
	v_sub_f32_e32 v99, v99, v133
	v_sub_f32_e32 v100, v100, v133
	v_sub_f32_e32 v101, v101, v133
	v_sub_f32_e32 v102, v102, v133
	v_sub_f32_e32 v103, v103, v133
	v_sub_f32_e32 v104, v104, v133
	v_sub_f32_e32 v105, v105, v133
	v_sub_f32_e32 v106, v106, v133
	v_sub_f32_e32 v107, v107, v133
	v_pk_mul_f32 v[82:83], v[82:83], v[134:135] op_sel_hi:[1,0]
	v_pk_mul_f32 v[80:81], v[80:81], v[134:135] op_sel_hi:[1,0]
	v_pk_mul_f32 v[22:23], v[22:23], v[134:135] op_sel_hi:[1,0]
	v_pk_mul_f32 v[20:21], v[20:21], v[134:135] op_sel_hi:[1,0]
	v_pk_mul_f32 v[30:31], v[30:31], v[134:135] op_sel_hi:[1,0]
	v_pk_mul_f32 v[28:29], v[28:29], v[134:135] op_sel_hi:[1,0]
	v_pk_mul_f32 v[42:43], v[42:43], v[134:135] op_sel_hi:[1,0]
	v_pk_mul_f32 v[40:41], v[40:41], v[134:135] op_sel_hi:[1,0]
	v_pk_mul_f32 v[50:51], v[50:51], v[134:135] op_sel_hi:[1,0]
	v_pk_mul_f32 v[48:49], v[48:49], v[134:135] op_sel_hi:[1,0]
	v_pk_mul_f32 v[58:59], v[58:59], v[134:135] op_sel_hi:[1,0]
	v_pk_mul_f32 v[56:57], v[56:57], v[134:135] op_sel_hi:[1,0]
	v_pk_mul_f32 v[66:67], v[66:67], v[134:135] op_sel_hi:[1,0]
	v_pk_mul_f32 v[64:65], v[64:65], v[134:135] op_sel_hi:[1,0]
	v_pk_mul_f32 v[74:75], v[74:75], v[134:135] op_sel_hi:[1,0]
	v_pk_mul_f32 v[72:73], v[72:73], v[134:135] op_sel_hi:[1,0]
	v_pk_mul_f32 v[78:79], v[78:79], v[134:135] op_sel_hi:[1,0]
	v_pk_mul_f32 v[76:77], v[76:77], v[134:135] op_sel_hi:[1,0]
.Lds_join:
	ds_read_b128 v[222:225], v137 offset:20480
	s_waitcnt lgkmcnt(2)
	v_mfma_f32_16x16x32_bf16 v[68:71], v[214:217], v[128:131], v[68:71]
	v_exp_f32_e32 v92, v92
	v_exp_f32_e32 v93, v93
	v_exp_f32_e32 v94, v94
	ds_read_b128 v[226:229], v137 offset:22528
	s_waitcnt lgkmcnt(2)
	v_mfma_f32_16x16x32_bf16 v[60:63], v[218:221], v[128:131], v[60:63]
	v_exp_f32_e32 v95, v95
	v_exp_f32_e32 v96, v96
	ds_read_b128 v[230:233], v137 offset:24576
	s_waitcnt lgkmcnt(2)
	v_mfma_f32_16x16x32_bf16 v[52:55], v[222:225], v[128:131], v[52:55]
	v_exp_f32_e32 v97, v97
	v_exp_f32_e32 v98, v98
	v_exp_f32_e32 v99, v99
	ds_read_b128 v[234:237], v137 offset:26624
	s_waitcnt lgkmcnt(2)
	v_mfma_f32_16x16x32_bf16 v[44:47], v[226:229], v[128:131], v[44:47]
	v_exp_f32_e32 v100, v100
	v_exp_f32_e32 v101, v101
	v_exp_f32_e32 v102, v102
	ds_read_b128 v[238:241], v137 offset:28672
	s_waitcnt lgkmcnt(2)
	v_mfma_f32_16x16x32_bf16 v[36:39], v[230:233], v[128:131], v[36:39]
	v_exp_f32_e32 v103, v103
	v_exp_f32_e32 v104, v104
	ds_read_b128 v[242:245], v137 offset:30720
	s_waitcnt lgkmcnt(2)
	v_mfma_f32_16x16x32_bf16 v[32:35], v[234:237], v[128:131], v[32:35]
	v_exp_f32_e32 v105, v105
	v_exp_f32_e32 v106, v106
	v_exp_f32_e32 v107, v107
	s_waitcnt lgkmcnt(1)
	v_mfma_f32_16x16x32_bf16 v[24:27], v[238:241], v[128:131], v[24:27]
	v_cvt_pk_bf16_f32 v92, v92, v93
	v_cvt_pk_bf16_f32 v93, v94, v95
	v_cvt_pk_bf16_f32 v94, v96, v97
	s_waitcnt lgkmcnt(0)
	v_mfma_f32_16x16x32_bf16 v[84:87], v[242:245], v[128:131], v[84:87]
	v_cvt_pk_bf16_f32 v95, v98, v99
	v_cvt_pk_bf16_f32 v100, v100, v101
	v_mfma_f32_16x16x32_bf16 v[88:91], v[120:123], v[128:131], v[88:91]
	v_cvt_pk_bf16_f32 v101, v102, v103
	v_cvt_pk_bf16_f32 v102, v104, v105
	v_cvt_pk_bf16_f32 v103, v106, v107
	v_mov_b64_e32 v[246:247], v[92:93]
	v_mov_b64_e32 v[248:249], v[94:95]
	v_mov_b64_e32 v[250:251], v[100:101]
	v_mov_b64_e32 v[252:253], v[102:103]
	s_mov_b32 s98, 1
	s_branch .LBB0_1620
.LBB0_1626:
	s_cmp_lg_u32 s98, 0
	s_cbranch_scc0 .Ldf_nodrain
	v_mfma_f32_16x16x32_bf16 v[72:75], v[182:185], v[246:249], v[72:75]
	v_mfma_f32_16x16x32_bf16 v[64:67], v[186:189], v[246:249], v[64:67]
	v_mfma_f32_16x16x32_bf16 v[56:59], v[190:193], v[246:249], v[56:59]
	v_mfma_f32_16x16x32_bf16 v[48:51], v[194:197], v[246:249], v[48:51]
	v_mfma_f32_16x16x32_bf16 v[40:43], v[198:201], v[246:249], v[40:43]
	v_mfma_f32_16x16x32_bf16 v[28:31], v[202:205], v[246:249], v[28:31]
	v_mfma_f32_16x16x32_bf16 v[20:23], v[206:209], v[246:249], v[20:23]
	v_mfma_f32_16x16x32_bf16 v[80:83], v[210:213], v[246:249], v[80:83]
	v_mfma_f32_16x16x32_bf16 v[76:79], v[120:123], v[246:249], v[76:79]
	v_mfma_f32_16x16x32_bf16 v[72:75], v[214:217], v[250:253], v[72:75]
	v_mfma_f32_16x16x32_bf16 v[64:67], v[218:221], v[250:253], v[64:67]
	v_mfma_f32_16x16x32_bf16 v[56:59], v[222:225], v[250:253], v[56:59]
	v_mfma_f32_16x16x32_bf16 v[48:51], v[226:229], v[250:253], v[48:51]
	v_mfma_f32_16x16x32_bf16 v[40:43], v[230:233], v[250:253], v[40:43]
	v_mfma_f32_16x16x32_bf16 v[28:31], v[234:237], v[250:253], v[28:31]
	v_mfma_f32_16x16x32_bf16 v[20:23], v[238:241], v[250:253], v[20:23]
	v_mfma_f32_16x16x32_bf16 v[80:83], v[242:245], v[250:253], v[80:83]
	v_mfma_f32_16x16x32_bf16 v[76:79], v[120:123], v[250:253], v[76:79]
	s_mov_b32 s98, 0
	s_nop 7
	s_nop 7
